# code placement: nine hot GEMM K-loop heads aligned to 64 bytes
# baseline (speedup 1.0000x reference)
.LBB0_110:
	s_ashr_i32 s19, s18, 31
	s_lshl_b64 s[20:21], s[18:19], 19
	s_add_u32 s20, s38, s20
	s_addc_u32 s21, s39, s21
	s_and_b64 s[22:23], s[2:3], exec
	s_cselect_b32 s19, s21, s27
	s_cselect_b32 s52, s20, s26
	s_ashr_i32 s17, s16, 31
	s_lshl_b64 s[22:23], s[16:17], 19
	s_add_u32 s22, s40, s22
	s_addc_u32 s23, s41, s23
	s_and_b64 s[30:31], s[2:3], exec
	s_cselect_b32 s17, s23, s29
	s_cselect_b32 s53, s22, s28
	s_add_u32 s26, s26, 0x40080
	s_addc_u32 s27, s27, 0
	s_add_u32 s54, s28, 0x100
	v_mov_b32_e32 v2, 0
	s_addc_u32 s55, s29, 0
	s_mov_b32 s56, -2
	v_mov_b32_e32 v3, v2
	v_mov_b32_e32 v4, v2
	v_mov_b32_e32 v5, v2
	v_mov_b32_e32 v6, v2
	v_mov_b32_e32 v7, v2
	v_mov_b32_e32 v8, v2
	v_mov_b32_e32 v9, v2
	v_mov_b32_e32 v18, v2
	v_mov_b32_e32 v19, v2
	v_mov_b32_e32 v20, v2
	v_mov_b32_e32 v21, v2
	v_mov_b32_e32 v22, v2
	v_mov_b32_e32 v23, v2
	v_mov_b32_e32 v24, v2
	v_mov_b32_e32 v25, v2
	v_mov_b32_e32 v34, v2
	v_mov_b32_e32 v35, v2
	v_mov_b32_e32 v36, v2
	v_mov_b32_e32 v37, v2
	v_mov_b32_e32 v38, v2
	v_mov_b32_e32 v39, v2
	v_mov_b32_e32 v40, v2
	v_mov_b32_e32 v41, v2
	v_mov_b32_e32 v50, v2
	v_mov_b32_e32 v51, v2
	v_mov_b32_e32 v52, v2
	v_mov_b32_e32 v53, v2
	v_mov_b32_e32 v54, v2
	v_mov_b32_e32 v55, v2
	v_mov_b32_e32 v56, v2
	v_mov_b32_e32 v57, v2
	v_mov_b32_e32 v10, v2
	v_mov_b32_e32 v11, v2
	v_mov_b32_e32 v12, v2
	v_mov_b32_e32 v13, v2
	v_mov_b32_e32 v14, v2
	v_mov_b32_e32 v15, v2
	v_mov_b32_e32 v16, v2
	v_mov_b32_e32 v17, v2
	v_mov_b32_e32 v26, v2
	v_mov_b32_e32 v27, v2
	v_mov_b32_e32 v28, v2
	v_mov_b32_e32 v29, v2
	v_mov_b32_e32 v30, v2
	v_mov_b32_e32 v31, v2
	v_mov_b32_e32 v32, v2
	v_mov_b32_e32 v33, v2
	v_mov_b32_e32 v42, v2
	v_mov_b32_e32 v43, v2
	v_mov_b32_e32 v44, v2
	v_mov_b32_e32 v45, v2
	v_mov_b32_e32 v46, v2
	v_mov_b32_e32 v47, v2
	v_mov_b32_e32 v48, v2
	v_mov_b32_e32 v49, v2
	v_mov_b32_e32 v58, v2
	v_mov_b32_e32 v59, v2
	v_mov_b32_e32 v60, v2
	v_mov_b32_e32 v61, v2
	v_mov_b32_e32 v62, v2
	v_mov_b32_e32 v63, v2
	v_mov_b32_e32 v64, v2
	v_mov_b32_e32 v65, v2
	v_mov_b32_e32 v66, v2
	v_mov_b32_e32 v67, v2
	v_mov_b32_e32 v68, v2
	v_mov_b32_e32 v69, v2
	v_mov_b32_e32 v70, v2
	v_mov_b32_e32 v71, v2
	v_mov_b32_e32 v72, v2
	v_mov_b32_e32 v73, v2
	v_mov_b32_e32 v82, v2
	v_mov_b32_e32 v83, v2
	v_mov_b32_e32 v84, v2
	v_mov_b32_e32 v85, v2
	v_mov_b32_e32 v86, v2
	v_mov_b32_e32 v87, v2
	v_mov_b32_e32 v88, v2
	v_mov_b32_e32 v89, v2
	v_mov_b32_e32 v98, v2
	v_mov_b32_e32 v99, v2
	v_mov_b32_e32 v100, v2
	v_mov_b32_e32 v101, v2
	v_mov_b32_e32 v102, v2
	v_mov_b32_e32 v103, v2
	v_mov_b32_e32 v104, v2
	v_mov_b32_e32 v105, v2
	v_mov_b32_e32 v114, v2
	v_mov_b32_e32 v115, v2
	v_mov_b32_e32 v116, v2
	v_mov_b32_e32 v117, v2
	v_mov_b32_e32 v118, v2
	v_mov_b32_e32 v119, v2
	v_mov_b32_e32 v120, v2
	v_mov_b32_e32 v121, v2
	v_mov_b32_e32 v74, v2
	v_mov_b32_e32 v75, v2
	v_mov_b32_e32 v76, v2
	v_mov_b32_e32 v77, v2
	v_mov_b32_e32 v78, v2
	v_mov_b32_e32 v79, v2
	v_mov_b32_e32 v80, v2
	v_mov_b32_e32 v81, v2
	v_mov_b32_e32 v90, v2
	v_mov_b32_e32 v91, v2
	v_mov_b32_e32 v92, v2
	v_mov_b32_e32 v93, v2
	v_mov_b32_e32 v94, v2
	v_mov_b32_e32 v95, v2
	v_mov_b32_e32 v96, v2
	v_mov_b32_e32 v97, v2
	v_mov_b32_e32 v106, v2
	v_mov_b32_e32 v107, v2
	v_mov_b32_e32 v108, v2
	v_mov_b32_e32 v109, v2
	v_mov_b32_e32 v110, v2
	v_mov_b32_e32 v111, v2
	v_mov_b32_e32 v112, v2
	v_mov_b32_e32 v113, v2
	v_mov_b32_e32 v122, v2
	v_mov_b32_e32 v123, v2
	v_mov_b32_e32 v124, v2
	v_mov_b32_e32 v125, v2
	v_mov_b32_e32 v126, v2
	v_mov_b32_e32 v127, v2
	v_mov_b32_e32 v128, v2
	v_mov_b32_e32 v129, v2
	.p2align	6

.LBB0_219:
	s_add_u32 s56, s26, 0x100
	v_mov_b32_e32 v2, 0
	s_addc_u32 s57, s27, 0
	s_mov_b32 s58, -2
	s_waitcnt lgkmcnt(0)
	v_mov_b32_e32 v3, v2
	v_mov_b32_e32 v4, v2
	v_mov_b32_e32 v5, v2
	v_mov_b32_e32 v6, v2
	v_mov_b32_e32 v7, v2
	v_mov_b32_e32 v8, v2
	v_mov_b32_e32 v9, v2
	v_mov_b32_e32 v18, v2
	v_mov_b32_e32 v19, v2
	v_mov_b32_e32 v20, v2
	v_mov_b32_e32 v21, v2
	v_mov_b32_e32 v22, v2
	v_mov_b32_e32 v23, v2
	v_mov_b32_e32 v24, v2
	v_mov_b32_e32 v25, v2
	v_mov_b32_e32 v34, v2
	v_mov_b32_e32 v35, v2
	v_mov_b32_e32 v36, v2
	v_mov_b32_e32 v37, v2
	v_mov_b32_e32 v38, v2
	v_mov_b32_e32 v39, v2
	v_mov_b32_e32 v40, v2
	v_mov_b32_e32 v41, v2
	v_mov_b32_e32 v50, v2
	v_mov_b32_e32 v51, v2
	v_mov_b32_e32 v52, v2
	v_mov_b32_e32 v53, v2
	v_mov_b32_e32 v54, v2
	v_mov_b32_e32 v55, v2
	v_mov_b32_e32 v56, v2
	v_mov_b32_e32 v57, v2
	v_mov_b32_e32 v10, v2
	v_mov_b32_e32 v11, v2
	v_mov_b32_e32 v12, v2
	v_mov_b32_e32 v13, v2
	v_mov_b32_e32 v14, v2
	v_mov_b32_e32 v15, v2
	v_mov_b32_e32 v16, v2
	v_mov_b32_e32 v17, v2
	v_mov_b32_e32 v26, v2
	v_mov_b32_e32 v27, v2
	v_mov_b32_e32 v28, v2
	v_mov_b32_e32 v29, v2
	v_mov_b32_e32 v30, v2
	v_mov_b32_e32 v31, v2
	v_mov_b32_e32 v32, v2
	v_mov_b32_e32 v33, v2
	v_mov_b32_e32 v42, v2
	v_mov_b32_e32 v43, v2
	v_mov_b32_e32 v44, v2
	v_mov_b32_e32 v45, v2
	v_mov_b32_e32 v46, v2
	v_mov_b32_e32 v47, v2
	v_mov_b32_e32 v48, v2
	v_mov_b32_e32 v49, v2
	v_mov_b32_e32 v58, v2
	v_mov_b32_e32 v59, v2
	v_mov_b32_e32 v60, v2
	v_mov_b32_e32 v61, v2
	v_mov_b32_e32 v62, v2
	v_mov_b32_e32 v63, v2
	v_mov_b32_e32 v64, v2
	v_mov_b32_e32 v65, v2
	v_mov_b32_e32 v66, v2
	v_mov_b32_e32 v67, v2
	v_mov_b32_e32 v68, v2
	v_mov_b32_e32 v69, v2
	v_mov_b32_e32 v70, v2
	v_mov_b32_e32 v71, v2
	v_mov_b32_e32 v72, v2
	v_mov_b32_e32 v73, v2
	v_mov_b32_e32 v82, v2
	v_mov_b32_e32 v83, v2
	v_mov_b32_e32 v84, v2
	v_mov_b32_e32 v85, v2
	v_mov_b32_e32 v86, v2
	v_mov_b32_e32 v87, v2
	v_mov_b32_e32 v88, v2
	v_mov_b32_e32 v89, v2
	v_mov_b32_e32 v98, v2
	v_mov_b32_e32 v99, v2
	v_mov_b32_e32 v100, v2
	v_mov_b32_e32 v101, v2
	v_mov_b32_e32 v102, v2
	v_mov_b32_e32 v103, v2
	v_mov_b32_e32 v104, v2
	v_mov_b32_e32 v105, v2
	v_mov_b32_e32 v126, v2
	v_mov_b32_e32 v127, v2
	v_mov_b32_e32 v128, v2
	v_mov_b32_e32 v129, v2
	v_mov_b32_e32 v130, v2
	v_mov_b32_e32 v131, v2
	v_mov_b32_e32 v132, v2
	v_mov_b32_e32 v133, v2
	v_mov_b32_e32 v74, v2
	v_mov_b32_e32 v75, v2
	v_mov_b32_e32 v76, v2
	v_mov_b32_e32 v77, v2
	v_mov_b32_e32 v78, v2
	v_mov_b32_e32 v79, v2
	v_mov_b32_e32 v80, v2
	v_mov_b32_e32 v81, v2
	v_mov_b32_e32 v90, v2
	v_mov_b32_e32 v91, v2
	v_mov_b32_e32 v92, v2
	v_mov_b32_e32 v93, v2
	v_mov_b32_e32 v94, v2
	v_mov_b32_e32 v95, v2
	v_mov_b32_e32 v96, v2
	v_mov_b32_e32 v97, v2
	v_mov_b32_e32 v106, v2
	v_mov_b32_e32 v107, v2
	v_mov_b32_e32 v108, v2
	v_mov_b32_e32 v109, v2
	v_mov_b32_e32 v114, v2
	v_mov_b32_e32 v115, v2
	v_mov_b32_e32 v116, v2
	v_mov_b32_e32 v117, v2
	v_mov_b32_e32 v150, v2
	v_mov_b32_e32 v151, v2
	v_mov_b32_e32 v152, v2
	v_mov_b32_e32 v153, v2
	v_mov_b32_e32 v158, v2
	v_mov_b32_e32 v159, v2
	v_mov_b32_e32 v160, v2
	v_mov_b32_e32 v161, v2
	.p2align	6

.LBB0_325:
	s_ashr_i32 s21, s20, 31
	s_lshl_b64 s[22:23], s[20:21], 19
	s_add_u32 s22, s40, s22
	s_addc_u32 s23, s41, s23
	s_and_b64 s[24:25], s[2:3], exec
	s_cselect_b32 s5, s23, s29
	s_cselect_b32 s21, s22, s28
	s_ashr_i32 s19, s18, 31
	s_lshl_b64 s[24:25], s[18:19], 19
	s_add_u32 s24, s42, s24
	s_addc_u32 s25, s43, s25
	s_and_b64 s[34:35], s[2:3], exec
	s_cselect_b32 s19, s25, s31
	s_cselect_b32 s36, s24, s30
	s_add_u32 s28, s28, 0x40080
	s_addc_u32 s29, s29, 0
	s_add_u32 s37, s30, 0x100
	v_mov_b32_e32 v2, 0
	s_addc_u32 s70, s31, 0
	s_mov_b32 s71, -2
	v_mov_b32_e32 v3, v2
	v_mov_b32_e32 v4, v2
	v_mov_b32_e32 v5, v2
	v_mov_b32_e32 v6, v2
	v_mov_b32_e32 v7, v2
	v_mov_b32_e32 v8, v2
	v_mov_b32_e32 v9, v2
	v_mov_b32_e32 v18, v2
	v_mov_b32_e32 v19, v2
	v_mov_b32_e32 v20, v2
	v_mov_b32_e32 v21, v2
	v_mov_b32_e32 v22, v2
	v_mov_b32_e32 v23, v2
	v_mov_b32_e32 v24, v2
	v_mov_b32_e32 v25, v2
	v_mov_b32_e32 v34, v2
	v_mov_b32_e32 v35, v2
	v_mov_b32_e32 v36, v2
	v_mov_b32_e32 v37, v2
	v_mov_b32_e32 v38, v2
	v_mov_b32_e32 v39, v2
	v_mov_b32_e32 v40, v2
	v_mov_b32_e32 v41, v2
	v_mov_b32_e32 v50, v2
	v_mov_b32_e32 v51, v2
	v_mov_b32_e32 v52, v2
	v_mov_b32_e32 v53, v2
	v_mov_b32_e32 v54, v2
	v_mov_b32_e32 v55, v2
	v_mov_b32_e32 v56, v2
	v_mov_b32_e32 v57, v2
	v_mov_b32_e32 v10, v2
	v_mov_b32_e32 v11, v2
	v_mov_b32_e32 v12, v2
	v_mov_b32_e32 v13, v2
	v_mov_b32_e32 v14, v2
	v_mov_b32_e32 v15, v2
	v_mov_b32_e32 v16, v2
	v_mov_b32_e32 v17, v2
	v_mov_b32_e32 v26, v2
	v_mov_b32_e32 v27, v2
	v_mov_b32_e32 v28, v2
	v_mov_b32_e32 v29, v2
	v_mov_b32_e32 v30, v2
	v_mov_b32_e32 v31, v2
	v_mov_b32_e32 v32, v2
	v_mov_b32_e32 v33, v2
	v_mov_b32_e32 v42, v2
	v_mov_b32_e32 v43, v2
	v_mov_b32_e32 v44, v2
	v_mov_b32_e32 v45, v2
	v_mov_b32_e32 v46, v2
	v_mov_b32_e32 v47, v2
	v_mov_b32_e32 v48, v2
	v_mov_b32_e32 v49, v2
	v_mov_b32_e32 v58, v2
	v_mov_b32_e32 v59, v2
	v_mov_b32_e32 v60, v2
	v_mov_b32_e32 v61, v2
	v_mov_b32_e32 v62, v2
	v_mov_b32_e32 v63, v2
	v_mov_b32_e32 v64, v2
	v_mov_b32_e32 v65, v2
	v_mov_b32_e32 v66, v2
	v_mov_b32_e32 v67, v2
	v_mov_b32_e32 v68, v2
	v_mov_b32_e32 v69, v2
	v_mov_b32_e32 v70, v2
	v_mov_b32_e32 v71, v2
	v_mov_b32_e32 v72, v2
	v_mov_b32_e32 v73, v2
	v_mov_b32_e32 v82, v2
	v_mov_b32_e32 v83, v2
	v_mov_b32_e32 v84, v2
	v_mov_b32_e32 v85, v2
	v_mov_b32_e32 v86, v2
	v_mov_b32_e32 v87, v2
	v_mov_b32_e32 v88, v2
	v_mov_b32_e32 v89, v2
	v_mov_b32_e32 v98, v2
	v_mov_b32_e32 v99, v2
	v_mov_b32_e32 v100, v2
	v_mov_b32_e32 v101, v2
	v_mov_b32_e32 v102, v2
	v_mov_b32_e32 v103, v2
	v_mov_b32_e32 v104, v2
	v_mov_b32_e32 v105, v2
	v_mov_b32_e32 v114, v2
	v_mov_b32_e32 v115, v2
	v_mov_b32_e32 v116, v2
	v_mov_b32_e32 v117, v2
	v_mov_b32_e32 v118, v2
	v_mov_b32_e32 v119, v2
	v_mov_b32_e32 v120, v2
	v_mov_b32_e32 v121, v2
	v_mov_b32_e32 v74, v2
	v_mov_b32_e32 v75, v2
	v_mov_b32_e32 v76, v2
	v_mov_b32_e32 v77, v2
	v_mov_b32_e32 v78, v2
	v_mov_b32_e32 v79, v2
	v_mov_b32_e32 v80, v2
	v_mov_b32_e32 v81, v2
	v_mov_b32_e32 v90, v2
	v_mov_b32_e32 v91, v2
	v_mov_b32_e32 v92, v2
	v_mov_b32_e32 v93, v2
	v_mov_b32_e32 v94, v2
	v_mov_b32_e32 v95, v2
	v_mov_b32_e32 v96, v2
	v_mov_b32_e32 v97, v2
	v_mov_b32_e32 v106, v2
	v_mov_b32_e32 v107, v2
	v_mov_b32_e32 v108, v2
	v_mov_b32_e32 v109, v2
	v_mov_b32_e32 v110, v2
	v_mov_b32_e32 v111, v2
	v_mov_b32_e32 v112, v2
	v_mov_b32_e32 v113, v2
	v_mov_b32_e32 v122, v2
	v_mov_b32_e32 v123, v2
	v_mov_b32_e32 v124, v2
	v_mov_b32_e32 v125, v2
	v_mov_b32_e32 v126, v2
	v_mov_b32_e32 v127, v2
	v_mov_b32_e32 v128, v2
	v_mov_b32_e32 v129, v2
	.p2align	6

.LBB0_806:
	s_ashr_i32 s19, s18, 31
	s_lshl_b64 s[20:21], s[18:19], 19
	s_add_u32 s20, s4, s20
	s_addc_u32 s21, s5, s21
	s_and_b64 s[22:23], s[2:3], exec
	s_cselect_b32 s19, s21, s27
	s_cselect_b32 s25, s20, s26
	s_ashr_i32 s17, s16, 31
	s_lshl_b64 s[22:23], s[16:17], 19
	s_add_u32 s22, s42, s22
	s_addc_u32 s23, s43, s23
	s_and_b64 s[30:31], s[2:3], exec
	s_cselect_b32 s17, s23, s35
	s_cselect_b32 s60, s22, s34
	s_ashr_i32 s29, s28, 31
	s_lshl_b64 s[30:31], s[28:29], 17
	s_add_u32 s29, s57, s30
	s_addc_u32 s61, s58, s31
	s_add_u32 s36, s26, 0x40080
	s_addc_u32 s37, s27, 0
	s_add_u32 s62, s34, 0x100
	v_mov_b32_e32 v2, 0
	v_lshl_add_u64 v[206:207], s[36:37], 0, v[194:195]
	v_lshl_add_u64 v[208:209], s[36:37], 0, v[204:205]
	s_addc_u32 s63, s35, 0
	s_mov_b32 s64, 0
	s_mov_b64 s[34:35], 0
	v_mov_b32_e32 v3, v2
	v_mov_b32_e32 v4, v2
	v_mov_b32_e32 v5, v2
	v_mov_b32_e32 v6, v2
	v_mov_b32_e32 v7, v2
	v_mov_b32_e32 v8, v2
	v_mov_b32_e32 v9, v2
	v_mov_b32_e32 v18, v2
	v_mov_b32_e32 v19, v2
	v_mov_b32_e32 v20, v2
	v_mov_b32_e32 v21, v2
	v_mov_b32_e32 v22, v2
	v_mov_b32_e32 v23, v2
	v_mov_b32_e32 v24, v2
	v_mov_b32_e32 v25, v2
	v_mov_b32_e32 v34, v2
	v_mov_b32_e32 v35, v2
	v_mov_b32_e32 v36, v2
	v_mov_b32_e32 v37, v2
	v_mov_b32_e32 v38, v2
	v_mov_b32_e32 v39, v2
	v_mov_b32_e32 v40, v2
	v_mov_b32_e32 v41, v2
	v_mov_b32_e32 v50, v2
	v_mov_b32_e32 v51, v2
	v_mov_b32_e32 v52, v2
	v_mov_b32_e32 v53, v2
	v_mov_b32_e32 v54, v2
	v_mov_b32_e32 v55, v2
	v_mov_b32_e32 v56, v2
	v_mov_b32_e32 v57, v2
	v_mov_b32_e32 v10, v2
	v_mov_b32_e32 v11, v2
	v_mov_b32_e32 v12, v2
	v_mov_b32_e32 v13, v2
	v_mov_b32_e32 v14, v2
	v_mov_b32_e32 v15, v2
	v_mov_b32_e32 v16, v2
	v_mov_b32_e32 v17, v2
	v_mov_b32_e32 v26, v2
	v_mov_b32_e32 v27, v2
	v_mov_b32_e32 v28, v2
	v_mov_b32_e32 v29, v2
	v_mov_b32_e32 v30, v2
	v_mov_b32_e32 v31, v2
	v_mov_b32_e32 v32, v2
	v_mov_b32_e32 v33, v2
	v_mov_b32_e32 v42, v2
	v_mov_b32_e32 v43, v2
	v_mov_b32_e32 v44, v2
	v_mov_b32_e32 v45, v2
	v_mov_b32_e32 v46, v2
	v_mov_b32_e32 v47, v2
	v_mov_b32_e32 v48, v2
	v_mov_b32_e32 v49, v2
	v_mov_b32_e32 v58, v2
	v_mov_b32_e32 v59, v2
	v_mov_b32_e32 v60, v2
	v_mov_b32_e32 v61, v2
	v_mov_b32_e32 v62, v2
	v_mov_b32_e32 v63, v2
	v_mov_b32_e32 v64, v2
	v_mov_b32_e32 v65, v2
	v_mov_b32_e32 v66, v2
	v_mov_b32_e32 v67, v2
	v_mov_b32_e32 v68, v2
	v_mov_b32_e32 v69, v2
	v_mov_b32_e32 v70, v2
	v_mov_b32_e32 v71, v2
	v_mov_b32_e32 v72, v2
	v_mov_b32_e32 v73, v2
	v_mov_b32_e32 v82, v2
	v_mov_b32_e32 v83, v2
	v_mov_b32_e32 v84, v2
	v_mov_b32_e32 v85, v2
	v_mov_b32_e32 v86, v2
	v_mov_b32_e32 v87, v2
	v_mov_b32_e32 v88, v2
	v_mov_b32_e32 v89, v2
	v_mov_b32_e32 v98, v2
	v_mov_b32_e32 v99, v2
	v_mov_b32_e32 v100, v2
	v_mov_b32_e32 v101, v2
	v_mov_b32_e32 v102, v2
	v_mov_b32_e32 v103, v2
	v_mov_b32_e32 v104, v2
	v_mov_b32_e32 v105, v2
	v_mov_b32_e32 v114, v2
	v_mov_b32_e32 v115, v2
	v_mov_b32_e32 v116, v2
	v_mov_b32_e32 v117, v2
	v_mov_b32_e32 v118, v2
	v_mov_b32_e32 v119, v2
	v_mov_b32_e32 v120, v2
	v_mov_b32_e32 v121, v2
	v_mov_b32_e32 v74, v2
	v_mov_b32_e32 v75, v2
	v_mov_b32_e32 v76, v2
	v_mov_b32_e32 v77, v2
	v_mov_b32_e32 v78, v2
	v_mov_b32_e32 v79, v2
	v_mov_b32_e32 v80, v2
	v_mov_b32_e32 v81, v2
	v_mov_b32_e32 v90, v2
	v_mov_b32_e32 v91, v2
	v_mov_b32_e32 v92, v2
	v_mov_b32_e32 v93, v2
	v_mov_b32_e32 v94, v2
	v_mov_b32_e32 v95, v2
	v_mov_b32_e32 v96, v2
	v_mov_b32_e32 v97, v2
	v_mov_b32_e32 v106, v2
	v_mov_b32_e32 v107, v2
	v_mov_b32_e32 v108, v2
	v_mov_b32_e32 v109, v2
	v_mov_b32_e32 v110, v2
	v_mov_b32_e32 v111, v2
	v_mov_b32_e32 v112, v2
	v_mov_b32_e32 v113, v2
	v_mov_b32_e32 v122, v2
	v_mov_b32_e32 v123, v2
	v_mov_b32_e32 v124, v2
	v_mov_b32_e32 v125, v2
	v_mov_b32_e32 v126, v2
	v_mov_b32_e32 v127, v2
	v_mov_b32_e32 v128, v2
	v_mov_b32_e32 v129, v2
	s_branch .LBB0_808
	.p2align	6

.LBB0_889:
	s_ashr_i32 s17, s16, 31
	s_lshl_b64 s[18:19], s[16:17], 19
	s_add_u32 s18, s36, s18
	s_addc_u32 s19, s37, s19
	s_and_b64 s[20:21], s[2:3], exec
	s_cselect_b32 s17, s19, s27
	s_cselect_b32 s23, s18, s26
	s_ashr_i32 s15, s14, 31
	s_lshl_b64 s[20:21], s[14:15], 19
	s_add_u32 s20, s38, s20
	s_addc_u32 s21, s39, s21
	s_and_b64 s[30:31], s[2:3], exec
	s_cselect_b32 s15, s21, s29
	s_cselect_b32 s51, s20, s28
	s_add_u32 s26, s26, 0x40080
	s_addc_u32 s27, s27, 0
	s_add_u32 s52, s28, 0x100
	v_mov_b32_e32 v2, 0
	s_addc_u32 s53, s29, 0
	s_mov_b32 s54, -2
	s_waitcnt lgkmcnt(0)
	v_mov_b32_e32 v3, v2
	v_mov_b32_e32 v4, v2
	v_mov_b32_e32 v5, v2
	v_mov_b32_e32 v6, v2
	v_mov_b32_e32 v7, v2
	v_mov_b32_e32 v8, v2
	v_mov_b32_e32 v9, v2
	v_mov_b32_e32 v18, v2
	v_mov_b32_e32 v19, v2
	v_mov_b32_e32 v20, v2
	v_mov_b32_e32 v21, v2
	v_mov_b32_e32 v22, v2
	v_mov_b32_e32 v23, v2
	v_mov_b32_e32 v24, v2
	v_mov_b32_e32 v25, v2
	v_mov_b32_e32 v34, v2
	v_mov_b32_e32 v35, v2
	v_mov_b32_e32 v36, v2
	v_mov_b32_e32 v37, v2
	v_mov_b32_e32 v38, v2
	v_mov_b32_e32 v39, v2
	v_mov_b32_e32 v40, v2
	v_mov_b32_e32 v41, v2
	v_mov_b32_e32 v50, v2
	v_mov_b32_e32 v51, v2
	v_mov_b32_e32 v52, v2
	v_mov_b32_e32 v53, v2
	v_mov_b32_e32 v54, v2
	v_mov_b32_e32 v55, v2
	v_mov_b32_e32 v56, v2
	v_mov_b32_e32 v57, v2
	v_mov_b32_e32 v10, v2
	v_mov_b32_e32 v11, v2
	v_mov_b32_e32 v12, v2
	v_mov_b32_e32 v13, v2
	v_mov_b32_e32 v14, v2
	v_mov_b32_e32 v15, v2
	v_mov_b32_e32 v16, v2
	v_mov_b32_e32 v17, v2
	v_mov_b32_e32 v26, v2
	v_mov_b32_e32 v27, v2
	v_mov_b32_e32 v28, v2
	v_mov_b32_e32 v29, v2
	v_mov_b32_e32 v30, v2
	v_mov_b32_e32 v31, v2
	v_mov_b32_e32 v32, v2
	v_mov_b32_e32 v33, v2
	v_mov_b32_e32 v42, v2
	v_mov_b32_e32 v43, v2
	v_mov_b32_e32 v44, v2
	v_mov_b32_e32 v45, v2
	v_mov_b32_e32 v46, v2
	v_mov_b32_e32 v47, v2
	v_mov_b32_e32 v48, v2
	v_mov_b32_e32 v49, v2
	v_mov_b32_e32 v58, v2
	v_mov_b32_e32 v59, v2
	v_mov_b32_e32 v60, v2
	v_mov_b32_e32 v61, v2
	v_mov_b32_e32 v62, v2
	v_mov_b32_e32 v63, v2
	v_mov_b32_e32 v64, v2
	v_mov_b32_e32 v65, v2
	v_mov_b32_e32 v66, v2
	v_mov_b32_e32 v67, v2
	v_mov_b32_e32 v68, v2
	v_mov_b32_e32 v69, v2
	v_mov_b32_e32 v70, v2
	v_mov_b32_e32 v71, v2
	v_mov_b32_e32 v72, v2
	v_mov_b32_e32 v73, v2
	v_mov_b32_e32 v82, v2
	v_mov_b32_e32 v83, v2
	v_mov_b32_e32 v84, v2
	v_mov_b32_e32 v85, v2
	v_mov_b32_e32 v86, v2
	v_mov_b32_e32 v87, v2
	v_mov_b32_e32 v88, v2
	v_mov_b32_e32 v89, v2
	v_mov_b32_e32 v98, v2
	v_mov_b32_e32 v99, v2
	v_mov_b32_e32 v100, v2
	v_mov_b32_e32 v101, v2
	v_mov_b32_e32 v102, v2
	v_mov_b32_e32 v103, v2
	v_mov_b32_e32 v104, v2
	v_mov_b32_e32 v105, v2
	v_mov_b32_e32 v126, v2
	v_mov_b32_e32 v127, v2
	v_mov_b32_e32 v128, v2
	v_mov_b32_e32 v129, v2
	v_mov_b32_e32 v130, v2
	v_mov_b32_e32 v131, v2
	v_mov_b32_e32 v132, v2
	v_mov_b32_e32 v133, v2
	v_mov_b32_e32 v74, v2
	v_mov_b32_e32 v75, v2
	v_mov_b32_e32 v76, v2
	v_mov_b32_e32 v77, v2
	v_mov_b32_e32 v78, v2
	v_mov_b32_e32 v79, v2
	v_mov_b32_e32 v80, v2
	v_mov_b32_e32 v81, v2
	v_mov_b32_e32 v90, v2
	v_mov_b32_e32 v91, v2
	v_mov_b32_e32 v92, v2
	v_mov_b32_e32 v93, v2
	v_mov_b32_e32 v94, v2
	v_mov_b32_e32 v95, v2
	v_mov_b32_e32 v96, v2
	v_mov_b32_e32 v97, v2
	v_mov_b32_e32 v106, v2
	v_mov_b32_e32 v107, v2
	v_mov_b32_e32 v108, v2
	v_mov_b32_e32 v109, v2
	v_mov_b32_e32 v114, v2
	v_mov_b32_e32 v115, v2
	v_mov_b32_e32 v116, v2
	v_mov_b32_e32 v117, v2
	v_mov_b32_e32 v150, v2
	v_mov_b32_e32 v151, v2
	v_mov_b32_e32 v152, v2
	v_mov_b32_e32 v153, v2
	v_mov_b32_e32 v158, v2
	v_mov_b32_e32 v159, v2
	v_mov_b32_e32 v160, v2
	v_mov_b32_e32 v161, v2
	.p2align	6

.LBB0_983:
	s_ashr_i32 s19, s18, 31
	s_lshl_b64 s[20:21], s[18:19], 19
	s_add_u32 s20, s36, s20
	s_addc_u32 s21, s37, s21
	s_and_b64 s[22:23], s[2:3], exec
	s_cselect_b32 s19, s21, s5
	s_cselect_b32 s53, s20, s4
	s_ashr_i32 s22, s18, 4
	s_ashr_i32 s23, s22, 31
	s_lshl_b64 s[22:23], s[22:23], 21
	s_add_u32 s30, s38, s22
	s_addc_u32 s31, s39, s23
	s_ashr_i32 s17, s16, 31
	s_lshl_b64 s[22:23], s[16:17], 19
	s_add_u32 s22, s30, s22
	s_addc_u32 s23, s31, s23
	s_and_b64 s[30:31], s[2:3], exec
	s_cselect_b32 s17, s23, s29
	s_cselect_b32 s54, s22, s28
	s_add_u32 s4, s4, 0x40080
	s_addc_u32 s5, s5, 0
	s_add_u32 s55, s28, 0x100
	v_mov_b32_e32 v2, 0
	s_addc_u32 s56, s29, 0
	s_mov_b32 s57, -2
	v_mov_b32_e32 v3, v2
	v_mov_b32_e32 v4, v2
	v_mov_b32_e32 v5, v2
	v_mov_b32_e32 v6, v2
	v_mov_b32_e32 v7, v2
	v_mov_b32_e32 v8, v2
	v_mov_b32_e32 v9, v2
	v_mov_b32_e32 v18, v2
	v_mov_b32_e32 v19, v2
	v_mov_b32_e32 v20, v2
	v_mov_b32_e32 v21, v2
	v_mov_b32_e32 v22, v2
	v_mov_b32_e32 v23, v2
	v_mov_b32_e32 v24, v2
	v_mov_b32_e32 v25, v2
	v_mov_b32_e32 v34, v2
	v_mov_b32_e32 v35, v2
	v_mov_b32_e32 v36, v2
	v_mov_b32_e32 v37, v2
	v_mov_b32_e32 v38, v2
	v_mov_b32_e32 v39, v2
	v_mov_b32_e32 v40, v2
	v_mov_b32_e32 v41, v2
	v_mov_b32_e32 v50, v2
	v_mov_b32_e32 v51, v2
	v_mov_b32_e32 v52, v2
	v_mov_b32_e32 v53, v2
	v_mov_b32_e32 v54, v2
	v_mov_b32_e32 v55, v2
	v_mov_b32_e32 v56, v2
	v_mov_b32_e32 v57, v2
	v_mov_b32_e32 v10, v2
	v_mov_b32_e32 v11, v2
	v_mov_b32_e32 v12, v2
	v_mov_b32_e32 v13, v2
	v_mov_b32_e32 v14, v2
	v_mov_b32_e32 v15, v2
	v_mov_b32_e32 v16, v2
	v_mov_b32_e32 v17, v2
	v_mov_b32_e32 v26, v2
	v_mov_b32_e32 v27, v2
	v_mov_b32_e32 v28, v2
	v_mov_b32_e32 v29, v2
	v_mov_b32_e32 v30, v2
	v_mov_b32_e32 v31, v2
	v_mov_b32_e32 v32, v2
	v_mov_b32_e32 v33, v2
	v_mov_b32_e32 v42, v2
	v_mov_b32_e32 v43, v2
	v_mov_b32_e32 v44, v2
	v_mov_b32_e32 v45, v2
	v_mov_b32_e32 v46, v2
	v_mov_b32_e32 v47, v2
	v_mov_b32_e32 v48, v2
	v_mov_b32_e32 v49, v2
	v_mov_b32_e32 v58, v2
	v_mov_b32_e32 v59, v2
	v_mov_b32_e32 v60, v2
	v_mov_b32_e32 v61, v2
	v_mov_b32_e32 v62, v2
	v_mov_b32_e32 v63, v2
	v_mov_b32_e32 v64, v2
	v_mov_b32_e32 v65, v2
	v_mov_b32_e32 v66, v2
	v_mov_b32_e32 v67, v2
	v_mov_b32_e32 v68, v2
	v_mov_b32_e32 v69, v2
	v_mov_b32_e32 v70, v2
	v_mov_b32_e32 v71, v2
	v_mov_b32_e32 v72, v2
	v_mov_b32_e32 v73, v2
	v_mov_b32_e32 v82, v2
	v_mov_b32_e32 v83, v2
	v_mov_b32_e32 v84, v2
	v_mov_b32_e32 v85, v2
	v_mov_b32_e32 v86, v2
	v_mov_b32_e32 v87, v2
	v_mov_b32_e32 v88, v2
	v_mov_b32_e32 v89, v2
	v_mov_b32_e32 v98, v2
	v_mov_b32_e32 v99, v2
	v_mov_b32_e32 v100, v2
	v_mov_b32_e32 v101, v2
	v_mov_b32_e32 v102, v2
	v_mov_b32_e32 v103, v2
	v_mov_b32_e32 v104, v2
	v_mov_b32_e32 v105, v2
	v_mov_b32_e32 v114, v2
	v_mov_b32_e32 v115, v2
	v_mov_b32_e32 v116, v2
	v_mov_b32_e32 v117, v2
	v_mov_b32_e32 v118, v2
	v_mov_b32_e32 v119, v2
	v_mov_b32_e32 v120, v2
	v_mov_b32_e32 v121, v2
	v_mov_b32_e32 v74, v2
	v_mov_b32_e32 v75, v2
	v_mov_b32_e32 v76, v2
	v_mov_b32_e32 v77, v2
	v_mov_b32_e32 v78, v2
	v_mov_b32_e32 v79, v2
	v_mov_b32_e32 v80, v2
	v_mov_b32_e32 v81, v2
	v_mov_b32_e32 v90, v2
	v_mov_b32_e32 v91, v2
	v_mov_b32_e32 v92, v2
	v_mov_b32_e32 v93, v2
	v_mov_b32_e32 v94, v2
	v_mov_b32_e32 v95, v2
	v_mov_b32_e32 v96, v2
	v_mov_b32_e32 v97, v2
	v_mov_b32_e32 v106, v2
	v_mov_b32_e32 v107, v2
	v_mov_b32_e32 v108, v2
	v_mov_b32_e32 v109, v2
	v_mov_b32_e32 v110, v2
	v_mov_b32_e32 v111, v2
	v_mov_b32_e32 v112, v2
	v_mov_b32_e32 v113, v2
	v_mov_b32_e32 v122, v2
	v_mov_b32_e32 v123, v2
	v_mov_b32_e32 v124, v2
	v_mov_b32_e32 v125, v2
	v_mov_b32_e32 v126, v2
	v_mov_b32_e32 v127, v2
	v_mov_b32_e32 v128, v2
	v_mov_b32_e32 v129, v2
	.p2align	6

.LBB0_1095:
	s_ashr_i32 s19, s18, 31
	s_lshl_b64 s[22:23], s[18:19], 19
	s_add_u32 s22, s36, s22
	s_addc_u32 s23, s37, s23
	s_and_b64 s[4:5], s[4:5], exec
	s_cselect_b32 s17, s23, s31
	s_cselect_b32 s19, s22, s30
	s_add_u32 s4, s30, 0x40080
	s_addc_u32 s5, s31, 0
	s_add_u32 s50, s28, 0x100
	v_mov_b32_e32 v2, 0
	s_addc_u32 s51, s29, 0
	s_mov_b32 s52, -2
	s_waitcnt lgkmcnt(0)
	v_mov_b32_e32 v3, v2
	v_mov_b32_e32 v4, v2
	v_mov_b32_e32 v5, v2
	v_mov_b32_e32 v6, v2
	v_mov_b32_e32 v7, v2
	v_mov_b32_e32 v8, v2
	v_mov_b32_e32 v9, v2
	v_mov_b32_e32 v18, v2
	v_mov_b32_e32 v19, v2
	v_mov_b32_e32 v20, v2
	v_mov_b32_e32 v21, v2
	v_mov_b32_e32 v22, v2
	v_mov_b32_e32 v23, v2
	v_mov_b32_e32 v24, v2
	v_mov_b32_e32 v25, v2
	v_mov_b32_e32 v34, v2
	v_mov_b32_e32 v35, v2
	v_mov_b32_e32 v36, v2
	v_mov_b32_e32 v37, v2
	v_mov_b32_e32 v38, v2
	v_mov_b32_e32 v39, v2
	v_mov_b32_e32 v40, v2
	v_mov_b32_e32 v41, v2
	v_mov_b32_e32 v50, v2
	v_mov_b32_e32 v51, v2
	v_mov_b32_e32 v52, v2
	v_mov_b32_e32 v53, v2
	v_mov_b32_e32 v54, v2
	v_mov_b32_e32 v55, v2
	v_mov_b32_e32 v56, v2
	v_mov_b32_e32 v57, v2
	v_mov_b32_e32 v10, v2
	v_mov_b32_e32 v11, v2
	v_mov_b32_e32 v12, v2
	v_mov_b32_e32 v13, v2
	v_mov_b32_e32 v14, v2
	v_mov_b32_e32 v15, v2
	v_mov_b32_e32 v16, v2
	v_mov_b32_e32 v17, v2
	v_mov_b32_e32 v26, v2
	v_mov_b32_e32 v27, v2
	v_mov_b32_e32 v28, v2
	v_mov_b32_e32 v29, v2
	v_mov_b32_e32 v30, v2
	v_mov_b32_e32 v31, v2
	v_mov_b32_e32 v32, v2
	v_mov_b32_e32 v33, v2
	v_mov_b32_e32 v42, v2
	v_mov_b32_e32 v43, v2
	v_mov_b32_e32 v44, v2
	v_mov_b32_e32 v45, v2
	v_mov_b32_e32 v46, v2
	v_mov_b32_e32 v47, v2
	v_mov_b32_e32 v48, v2
	v_mov_b32_e32 v49, v2
	v_mov_b32_e32 v58, v2
	v_mov_b32_e32 v59, v2
	v_mov_b32_e32 v60, v2
	v_mov_b32_e32 v61, v2
	v_mov_b32_e32 v62, v2
	v_mov_b32_e32 v63, v2
	v_mov_b32_e32 v64, v2
	v_mov_b32_e32 v65, v2
	v_mov_b32_e32 v66, v2
	v_mov_b32_e32 v67, v2
	v_mov_b32_e32 v68, v2
	v_mov_b32_e32 v69, v2
	v_mov_b32_e32 v70, v2
	v_mov_b32_e32 v71, v2
	v_mov_b32_e32 v72, v2
	v_mov_b32_e32 v73, v2
	v_mov_b32_e32 v82, v2
	v_mov_b32_e32 v83, v2
	v_mov_b32_e32 v84, v2
	v_mov_b32_e32 v85, v2
	v_mov_b32_e32 v86, v2
	v_mov_b32_e32 v87, v2
	v_mov_b32_e32 v88, v2
	v_mov_b32_e32 v89, v2
	v_mov_b32_e32 v98, v2
	v_mov_b32_e32 v99, v2
	v_mov_b32_e32 v100, v2
	v_mov_b32_e32 v101, v2
	v_mov_b32_e32 v102, v2
	v_mov_b32_e32 v103, v2
	v_mov_b32_e32 v104, v2
	v_mov_b32_e32 v105, v2
	v_mov_b32_e32 v126, v2
	v_mov_b32_e32 v127, v2
	v_mov_b32_e32 v128, v2
	v_mov_b32_e32 v129, v2
	v_mov_b32_e32 v130, v2
	v_mov_b32_e32 v131, v2
	v_mov_b32_e32 v132, v2
	v_mov_b32_e32 v133, v2
	v_mov_b32_e32 v74, v2
	v_mov_b32_e32 v75, v2
	v_mov_b32_e32 v76, v2
	v_mov_b32_e32 v77, v2
	v_mov_b32_e32 v78, v2
	v_mov_b32_e32 v79, v2
	v_mov_b32_e32 v80, v2
	v_mov_b32_e32 v81, v2
	v_mov_b32_e32 v90, v2
	v_mov_b32_e32 v91, v2
	v_mov_b32_e32 v92, v2
	v_mov_b32_e32 v93, v2
	v_mov_b32_e32 v94, v2
	v_mov_b32_e32 v95, v2
	v_mov_b32_e32 v96, v2
	v_mov_b32_e32 v97, v2
	v_mov_b32_e32 v106, v2
	v_mov_b32_e32 v107, v2
	v_mov_b32_e32 v108, v2
	v_mov_b32_e32 v109, v2
	v_mov_b32_e32 v114, v2
	v_mov_b32_e32 v115, v2
	v_mov_b32_e32 v116, v2
	v_mov_b32_e32 v117, v2
	v_mov_b32_e32 v150, v2
	v_mov_b32_e32 v151, v2
	v_mov_b32_e32 v152, v2
	v_mov_b32_e32 v153, v2
	v_mov_b32_e32 v158, v2
	v_mov_b32_e32 v159, v2
	v_mov_b32_e32 v160, v2
	v_mov_b32_e32 v161, v2
	.p2align	6

.LBB0_1179:
	s_ashr_i32 s17, s16, 31
	s_lshl_b64 s[18:19], s[16:17], 19
	s_add_u32 s18, s34, s18
	s_addc_u32 s19, s35, s19
	s_and_b64 s[20:21], s[2:3], exec
	s_cselect_b32 s17, s19, s25
	s_cselect_b32 s50, s18, s24
	s_ashr_i32 s15, s14, 31
	s_lshl_b64 s[20:21], s[14:15], 19
	s_add_u32 s20, s36, s20
	s_addc_u32 s21, s37, s21
	s_and_b64 s[28:29], s[2:3], exec
	s_cselect_b32 s15, s21, s27
	s_cselect_b32 s51, s20, s26
	s_add_u32 s24, s24, 0x40080
	s_addc_u32 s25, s25, 0
	s_add_u32 s52, s26, 0x100
	v_mov_b32_e32 v2, 0
	s_addc_u32 s53, s27, 0
	s_mov_b32 s54, -2
	v_mov_b32_e32 v3, v2
	v_mov_b32_e32 v4, v2
	v_mov_b32_e32 v5, v2
	v_mov_b32_e32 v6, v2
	v_mov_b32_e32 v7, v2
	v_mov_b32_e32 v8, v2
	v_mov_b32_e32 v9, v2
	v_mov_b32_e32 v18, v2
	v_mov_b32_e32 v19, v2
	v_mov_b32_e32 v20, v2
	v_mov_b32_e32 v21, v2
	v_mov_b32_e32 v22, v2
	v_mov_b32_e32 v23, v2
	v_mov_b32_e32 v24, v2
	v_mov_b32_e32 v25, v2
	v_mov_b32_e32 v34, v2
	v_mov_b32_e32 v35, v2
	v_mov_b32_e32 v36, v2
	v_mov_b32_e32 v37, v2
	v_mov_b32_e32 v38, v2
	v_mov_b32_e32 v39, v2
	v_mov_b32_e32 v40, v2
	v_mov_b32_e32 v41, v2
	v_mov_b32_e32 v50, v2
	v_mov_b32_e32 v51, v2
	v_mov_b32_e32 v52, v2
	v_mov_b32_e32 v53, v2
	v_mov_b32_e32 v54, v2
	v_mov_b32_e32 v55, v2
	v_mov_b32_e32 v56, v2
	v_mov_b32_e32 v57, v2
	v_mov_b32_e32 v10, v2
	v_mov_b32_e32 v11, v2
	v_mov_b32_e32 v12, v2
	v_mov_b32_e32 v13, v2
	v_mov_b32_e32 v14, v2
	v_mov_b32_e32 v15, v2
	v_mov_b32_e32 v16, v2
	v_mov_b32_e32 v17, v2
	v_mov_b32_e32 v26, v2
	v_mov_b32_e32 v27, v2
	v_mov_b32_e32 v28, v2
	v_mov_b32_e32 v29, v2
	v_mov_b32_e32 v30, v2
	v_mov_b32_e32 v31, v2
	v_mov_b32_e32 v32, v2
	v_mov_b32_e32 v33, v2
	v_mov_b32_e32 v42, v2
	v_mov_b32_e32 v43, v2
	v_mov_b32_e32 v44, v2
	v_mov_b32_e32 v45, v2
	v_mov_b32_e32 v46, v2
	v_mov_b32_e32 v47, v2
	v_mov_b32_e32 v48, v2
	v_mov_b32_e32 v49, v2
	v_mov_b32_e32 v58, v2
	v_mov_b32_e32 v59, v2
	v_mov_b32_e32 v60, v2
	v_mov_b32_e32 v61, v2
	v_mov_b32_e32 v62, v2
	v_mov_b32_e32 v63, v2
	v_mov_b32_e32 v64, v2
	v_mov_b32_e32 v65, v2
	v_mov_b32_e32 v66, v2
	v_mov_b32_e32 v67, v2
	v_mov_b32_e32 v68, v2
	v_mov_b32_e32 v69, v2
	v_mov_b32_e32 v70, v2
	v_mov_b32_e32 v71, v2
	v_mov_b32_e32 v72, v2
	v_mov_b32_e32 v73, v2
	v_mov_b32_e32 v82, v2
	v_mov_b32_e32 v83, v2
	v_mov_b32_e32 v84, v2
	v_mov_b32_e32 v85, v2
	v_mov_b32_e32 v86, v2
	v_mov_b32_e32 v87, v2
	v_mov_b32_e32 v88, v2
	v_mov_b32_e32 v89, v2
	v_mov_b32_e32 v98, v2
	v_mov_b32_e32 v99, v2
	v_mov_b32_e32 v100, v2
	v_mov_b32_e32 v101, v2
	v_mov_b32_e32 v102, v2
	v_mov_b32_e32 v103, v2
	v_mov_b32_e32 v104, v2
	v_mov_b32_e32 v105, v2
	v_mov_b32_e32 v114, v2
	v_mov_b32_e32 v115, v2
	v_mov_b32_e32 v116, v2
	v_mov_b32_e32 v117, v2
	v_mov_b32_e32 v118, v2
	v_mov_b32_e32 v119, v2
	v_mov_b32_e32 v120, v2
	v_mov_b32_e32 v121, v2
	v_mov_b32_e32 v74, v2
	v_mov_b32_e32 v75, v2
	v_mov_b32_e32 v76, v2
	v_mov_b32_e32 v77, v2
	v_mov_b32_e32 v78, v2
	v_mov_b32_e32 v79, v2
	v_mov_b32_e32 v80, v2
	v_mov_b32_e32 v81, v2
	v_mov_b32_e32 v90, v2
	v_mov_b32_e32 v91, v2
	v_mov_b32_e32 v92, v2
	v_mov_b32_e32 v93, v2
	v_mov_b32_e32 v94, v2
	v_mov_b32_e32 v95, v2
	v_mov_b32_e32 v96, v2
	v_mov_b32_e32 v97, v2
	v_mov_b32_e32 v106, v2
	v_mov_b32_e32 v107, v2
	v_mov_b32_e32 v108, v2
	v_mov_b32_e32 v109, v2
	v_mov_b32_e32 v110, v2
	v_mov_b32_e32 v111, v2
	v_mov_b32_e32 v112, v2
	v_mov_b32_e32 v113, v2
	v_mov_b32_e32 v122, v2
	v_mov_b32_e32 v123, v2
	v_mov_b32_e32 v124, v2
	v_mov_b32_e32 v125, v2
	v_mov_b32_e32 v126, v2
	v_mov_b32_e32 v127, v2
	v_mov_b32_e32 v128, v2
	v_mov_b32_e32 v129, v2
	s_waitcnt vmcnt(0)
	.p2align	6

.LBB0_1262:
	s_add_u32 s50, s20, 0x100
	v_mov_b32_e32 v2, 0
	s_addc_u32 s51, s21, 0
	s_mov_b32 s52, -2
	s_waitcnt lgkmcnt(0)
	v_mov_b32_e32 v3, v2
	v_mov_b32_e32 v4, v2
	v_mov_b32_e32 v5, v2
	v_mov_b32_e32 v6, v2
	v_mov_b32_e32 v7, v2
	v_mov_b32_e32 v8, v2
	v_mov_b32_e32 v9, v2
	v_mov_b32_e32 v18, v2
	v_mov_b32_e32 v19, v2
	v_mov_b32_e32 v20, v2
	v_mov_b32_e32 v21, v2
	v_mov_b32_e32 v22, v2
	v_mov_b32_e32 v23, v2
	v_mov_b32_e32 v24, v2
	v_mov_b32_e32 v25, v2
	v_mov_b32_e32 v34, v2
	v_mov_b32_e32 v35, v2
	v_mov_b32_e32 v36, v2
	v_mov_b32_e32 v37, v2
	v_mov_b32_e32 v38, v2
	v_mov_b32_e32 v39, v2
	v_mov_b32_e32 v40, v2
	v_mov_b32_e32 v41, v2
	v_mov_b32_e32 v50, v2
	v_mov_b32_e32 v51, v2
	v_mov_b32_e32 v52, v2
	v_mov_b32_e32 v53, v2
	v_mov_b32_e32 v54, v2
	v_mov_b32_e32 v55, v2
	v_mov_b32_e32 v56, v2
	v_mov_b32_e32 v57, v2
	v_mov_b32_e32 v10, v2
	v_mov_b32_e32 v11, v2
	v_mov_b32_e32 v12, v2
	v_mov_b32_e32 v13, v2
	v_mov_b32_e32 v14, v2
	v_mov_b32_e32 v15, v2
	v_mov_b32_e32 v16, v2
	v_mov_b32_e32 v17, v2
	v_mov_b32_e32 v26, v2
	v_mov_b32_e32 v27, v2
	v_mov_b32_e32 v28, v2
	v_mov_b32_e32 v29, v2
	v_mov_b32_e32 v30, v2
	v_mov_b32_e32 v31, v2
	v_mov_b32_e32 v32, v2
	v_mov_b32_e32 v33, v2
	v_mov_b32_e32 v42, v2
	v_mov_b32_e32 v43, v2
	v_mov_b32_e32 v44, v2
	v_mov_b32_e32 v45, v2
	v_mov_b32_e32 v46, v2
	v_mov_b32_e32 v47, v2
	v_mov_b32_e32 v48, v2
	v_mov_b32_e32 v49, v2
	v_mov_b32_e32 v58, v2
	v_mov_b32_e32 v59, v2
	v_mov_b32_e32 v60, v2
	v_mov_b32_e32 v61, v2
	v_mov_b32_e32 v62, v2
	v_mov_b32_e32 v63, v2
	v_mov_b32_e32 v64, v2
	v_mov_b32_e32 v65, v2
	v_mov_b32_e32 v66, v2
	v_mov_b32_e32 v67, v2
	v_mov_b32_e32 v68, v2
	v_mov_b32_e32 v69, v2
	v_mov_b32_e32 v70, v2
	v_mov_b32_e32 v71, v2
	v_mov_b32_e32 v72, v2
	v_mov_b32_e32 v73, v2
	v_mov_b32_e32 v82, v2
	v_mov_b32_e32 v83, v2
	v_mov_b32_e32 v84, v2
	v_mov_b32_e32 v85, v2
	v_mov_b32_e32 v86, v2
	v_mov_b32_e32 v87, v2
	v_mov_b32_e32 v88, v2
	v_mov_b32_e32 v89, v2
	v_mov_b32_e32 v98, v2
	v_mov_b32_e32 v99, v2
	v_mov_b32_e32 v100, v2
	v_mov_b32_e32 v101, v2
	v_mov_b32_e32 v102, v2
	v_mov_b32_e32 v103, v2
	v_mov_b32_e32 v104, v2
	v_mov_b32_e32 v105, v2
	v_mov_b32_e32 v126, v2
	v_mov_b32_e32 v127, v2
	v_mov_b32_e32 v128, v2
	v_mov_b32_e32 v129, v2
	v_mov_b32_e32 v130, v2
	v_mov_b32_e32 v131, v2
	v_mov_b32_e32 v132, v2
	v_mov_b32_e32 v133, v2
	v_mov_b32_e32 v74, v2
	v_mov_b32_e32 v75, v2
	v_mov_b32_e32 v76, v2
	v_mov_b32_e32 v77, v2
	v_mov_b32_e32 v78, v2
	v_mov_b32_e32 v79, v2
	v_mov_b32_e32 v80, v2
	v_mov_b32_e32 v81, v2
	v_mov_b32_e32 v90, v2
	v_mov_b32_e32 v91, v2
	v_mov_b32_e32 v92, v2
	v_mov_b32_e32 v93, v2
	v_mov_b32_e32 v94, v2
	v_mov_b32_e32 v95, v2
	v_mov_b32_e32 v96, v2
	v_mov_b32_e32 v97, v2
	v_mov_b32_e32 v106, v2
	v_mov_b32_e32 v107, v2
	v_mov_b32_e32 v108, v2
	v_mov_b32_e32 v109, v2
	v_mov_b32_e32 v114, v2
	v_mov_b32_e32 v115, v2
	v_mov_b32_e32 v116, v2
	v_mov_b32_e32 v117, v2
	v_mov_b32_e32 v150, v2
	v_mov_b32_e32 v151, v2
	v_mov_b32_e32 v152, v2
	v_mov_b32_e32 v153, v2
	v_mov_b32_e32 v158, v2
	v_mov_b32_e32 v159, v2
	v_mov_b32_e32 v160, v2
	v_mov_b32_e32 v161, v2
	.p2align	6
